# combined variant with six (instead of four) GQA fragment reads in flight ahead of the QK MFMAs
# speedup vs baseline: 1.0063x; 1.0063x over previous
.LBB0_580:
	ds_read_b128 v[32:35], v194
	ds_read_b128 v[36:39], v194 offset:4608
	ds_read_b128 v[96:99], v194 offset:32
	ds_read_b128 v[104:107], v194 offset:4640
	ds_read_b128 v[114:117], v194 offset:64
	ds_read_b128 v[122:125], v194 offset:4672
	s_waitcnt lgkmcnt(5)
	v_mfma_f32_32x32x16_bf16 v[48:63], v[32:35], v[64:67], 0
	s_add_i32 s15, s14, 1
	s_cmp_ge_u32 s15, s37
	ds_read_b128 v[118:121], v194 offset:96
	s_waitcnt lgkmcnt(5)
	v_mfma_f32_32x32x16_bf16 v[32:47], v[36:39], v[64:67], 0
	ds_read_b128 v[134:137], v194 offset:4704
	s_waitcnt lgkmcnt(5)
	v_mfma_f32_32x32x16_bf16 v[48:63], v[96:99], v[68:71], v[48:63]
	ds_read_b64_tr_b16 v[138:139], v218 offset:9216
	ds_read_b64_tr_b16 v[140:141], v218 offset:10240
	s_waitcnt lgkmcnt(6)
	v_mfma_f32_32x32x16_bf16 v[32:47], v[104:107], v[68:71], v[32:47]
	ds_read_b64_tr_b16 v[148:149], v218 offset:10496
	ds_read_b64_tr_b16 v[146:147], v218 offset:9472
	s_waitcnt lgkmcnt(7)
	v_mfma_f32_32x32x16_bf16 v[48:63], v[114:117], v[72:75], v[48:63]
	ds_read_b64_tr_b16 v[152:153], v218 offset:11264
	ds_read_b64_tr_b16 v[154:155], v218 offset:12288
	s_waitcnt lgkmcnt(8)
	v_mfma_f32_32x32x16_bf16 v[32:47], v[122:125], v[72:75], v[32:47]
	ds_read_b64_tr_b16 v[158:159], v218 offset:12544
	ds_read_b64_tr_b16 v[156:157], v218 offset:11520
	s_waitcnt lgkmcnt(9)
	v_mfma_f32_32x32x16_bf16 v[48:63], v[118:121], v[76:79], v[48:63]
	ds_read_b64_tr_b16 v[160:161], v218 offset:13312
	ds_read_b64_tr_b16 v[162:163], v218 offset:14336
	s_waitcnt lgkmcnt(10)
	v_mfma_f32_32x32x16_bf16 v[32:47], v[134:137], v[76:79], v[32:47]
	ds_read_b64_tr_b16 v[166:167], v218 offset:14592
	ds_read_b64_tr_b16 v[164:165], v218 offset:13568
	ds_read_b64_tr_b16 v[168:169], v218 offset:15360
	ds_read_b64_tr_b16 v[170:171], v218 offset:16384
	ds_read_b64_tr_b16 v[174:175], v218 offset:16640
	ds_read_b64_tr_b16 v[172:173], v218 offset:15616
	s_nop 10
	v_exp_f32_e32 v96, v48
	v_exp_f32_e32 v97, v49
	v_exp_f32_e32 v98, v50
	v_exp_f32_e32 v99, v51
	v_exp_f32_e32 v104, v52
	v_exp_f32_e32 v105, v53
	v_exp_f32_e32 v106, v54
	v_exp_f32_e32 v109, v32
	v_exp_f32_e32 v110, v33
	v_exp_f32_e32 v111, v34
	v_exp_f32_e32 v114, v35
	v_exp_f32_e32 v107, v55
	v_cvt_pk_bf16_f32 v32, v96, v97
	v_cvt_pk_bf16_f32 v33, v98, v99
	v_cvt_pk_bf16_f32 v34, v104, v105
	v_cvt_pk_bf16_f32 v35, v106, v107
	v_exp_f32_e32 v115, v36
	s_waitcnt lgkmcnt(14)
	v_mfma_f32_32x32x16_bf16 v[0:15], v[138:141], v[32:35], v[0:15]
	v_exp_f32_e32 v116, v37
	v_exp_f32_e32 v117, v38
	v_exp_f32_e32 v118, v39
	v_exp_f32_e32 v119, v56
	v_exp_f32_e32 v120, v57
	v_exp_f32_e32 v126, v58
	v_exp_f32_e32 v125, v59
	s_waitcnt lgkmcnt(12)
	v_mfma_f32_32x32x16_bf16 v[16:31], v[146:149], v[32:35], v[16:31]
	v_exp_f32_e32 v124, v60
	v_exp_f32_e32 v123, v61
	v_exp_f32_e32 v122, v62
	v_exp_f32_e32 v121, v63
	v_cvt_pk_bf16_f32 v36, v109, v110
	v_cvt_pk_bf16_f32 v37, v111, v114
	v_cvt_pk_bf16_f32 v38, v115, v116
	v_cvt_pk_bf16_f32 v39, v117, v118
	v_cvt_pk_bf16_f32 v32, v119, v120
	v_cvt_pk_bf16_f32 v33, v126, v125
	v_cvt_pk_bf16_f32 v34, v124, v123
	v_cvt_pk_bf16_f32 v35, v122, v121
	v_exp_f32_e32 v138, v40
	s_waitcnt lgkmcnt(10)
	v_mfma_f32_32x32x16_bf16 v[0:15], v[152:155], v[32:35], v[0:15]
	v_exp_f32_e32 v137, v41
	v_exp_f32_e32 v136, v42
	v_exp_f32_e32 v134, v43
	v_exp_f32_e32 v131, v44
	v_exp_f32_e32 v135, v45
	v_exp_f32_e32 v133, v46
	v_exp_f32_e32 v127, v47
	s_waitcnt lgkmcnt(8)
	v_mfma_f32_32x32x16_bf16 v[16:31], v[156:159], v[32:35], v[16:31]
	v_cvt_pk_bf16_f32 v32, v138, v137
	v_cvt_pk_bf16_f32 v33, v136, v134
	v_cvt_pk_bf16_f32 v34, v131, v135
	v_cvt_pk_bf16_f32 v35, v133, v127
	s_waitcnt lgkmcnt(6)
	v_mfma_f32_32x32x16_bf16 v[0:15], v[160:163], v[36:39], v[0:15]
	s_waitcnt lgkmcnt(4)
	v_mfma_f32_32x32x16_bf16 v[16:31], v[164:167], v[36:39], v[16:31]
	s_waitcnt lgkmcnt(2)
	v_mfma_f32_32x32x16_bf16 v[0:15], v[168:171], v[32:35], v[0:15]
	s_waitcnt lgkmcnt(0)
	v_mfma_f32_32x32x16_bf16 v[16:31], v[172:175], v[32:35], v[16:31]
	s_cbranch_scc1 .LBB0_582
	s_cmp_ge_u32 s13, s37
	s_cbranch_scc1 .Lgqa_w0_tail
	s_waitcnt vmcnt(3)
	ds_write_b128 v193, v[88:91] offset:17408
	s_waitcnt vmcnt(2)
	ds_write_b128 v219, v[92:95] offset:26624
	s_branch .LBB0_582

.LBB0_584:
	ds_read_b128 v[32:35], v194 offset:17408
	ds_read_b128 v[36:39], v194 offset:22016
	ds_read_b128 v[140:143], v194 offset:17440
	ds_read_b128 v[146:149], v194 offset:22048
	ds_read_b128 v[152:155], v194 offset:17472
	ds_read_b128 v[160:163], v194 offset:22080
	s_waitcnt lgkmcnt(5)
	v_mfma_f32_32x32x16_bf16 v[48:63], v[32:35], v[64:67], 0
	v_add_f32_e32 v222, v96, v97
	v_add_f32_e32 v223, v109, v110
	v_add_f32_e32 v222, v98, v222
	v_add_f32_e32 v223, v111, v223
	s_andn2_b64 vcc, exec, s[10:11]
	ds_read_b128 v[156:159], v194 offset:17504
	s_waitcnt lgkmcnt(5)
	v_mfma_f32_32x32x16_bf16 v[32:47], v[36:39], v[64:67], 0
	v_add_f32_e32 v222, v99, v222
	v_add_f32_e32 v223, v114, v223
	v_add_f32_e32 v222, v104, v222
	v_add_f32_e32 v223, v115, v223
	ds_read_b128 v[164:167], v194 offset:22112
	s_waitcnt lgkmcnt(5)
	v_mfma_f32_32x32x16_bf16 v[48:63], v[140:143], v[68:71], v[48:63]
	v_add_f32_e32 v222, v105, v222
	v_add_f32_e32 v223, v116, v223
	v_add_f32_e32 v222, v106, v222
	v_add_f32_e32 v223, v117, v223
	ds_read_b64_tr_b16 v[168:169], v218 offset:26624
	ds_read_b64_tr_b16 v[170:171], v218 offset:27648
	s_waitcnt lgkmcnt(6)
	v_mfma_f32_32x32x16_bf16 v[32:47], v[146:149], v[68:71], v[32:47]
	v_add_f32_e32 v222, v107, v222
	v_add_f32_e32 v223, v118, v223
	v_add_f32_e32 v222, v119, v222
	v_add_f32_e32 v223, v138, v223
	ds_read_b64_tr_b16 v[174:175], v218 offset:27904
	ds_read_b64_tr_b16 v[172:173], v218 offset:26880
	s_waitcnt lgkmcnt(7)
	v_mfma_f32_32x32x16_bf16 v[48:63], v[152:155], v[72:75], v[48:63]
	v_add_f32_e32 v222, v120, v222
	v_add_f32_e32 v223, v137, v223
	v_add_f32_e32 v222, v126, v222
	v_add_f32_e32 v223, v136, v223
	ds_read_b64_tr_b16 v[176:177], v218 offset:28672
	ds_read_b64_tr_b16 v[178:179], v218 offset:29696
	s_waitcnt lgkmcnt(8)
	v_mfma_f32_32x32x16_bf16 v[32:47], v[160:163], v[72:75], v[32:47]
	v_add_f32_e32 v222, v125, v222
	v_add_f32_e32 v223, v134, v223
	v_add_f32_e32 v222, v124, v222
	v_add_f32_e32 v223, v131, v223
	ds_read_b64_tr_b16 v[182:183], v218 offset:29952
	ds_read_b64_tr_b16 v[180:181], v218 offset:28928
	s_waitcnt lgkmcnt(9)
	v_mfma_f32_32x32x16_bf16 v[48:63], v[156:159], v[76:79], v[48:63]
	v_add_f32_e32 v222, v123, v222
	v_add_f32_e32 v223, v135, v223
	v_add_f32_e32 v222, v122, v222
	v_add_f32_e32 v223, v133, v223
	ds_read_b64_tr_b16 v[184:185], v218 offset:30720
	ds_read_b64_tr_b16 v[186:187], v218 offset:31744
	s_waitcnt lgkmcnt(10)
	v_mfma_f32_32x32x16_bf16 v[32:47], v[164:167], v[76:79], v[32:47]
	ds_read_b64_tr_b16 v[190:191], v218 offset:32000
	ds_read_b64_tr_b16 v[188:189], v218 offset:30976
	ds_read_b64_tr_b16 v[196:197], v218 offset:32768
	ds_read_b64_tr_b16 v[198:199], v218 offset:33792
	ds_read_b64_tr_b16 v[202:203], v218 offset:34048
	ds_read_b64_tr_b16 v[200:201], v218 offset:33024
	v_add_f32_e32 v222, v121, v222
	v_add_f32_e32 v223, v127, v223
	v_add_f32_e32 v222, v222, v223
	s_nop 10
	v_exp_f32_e32 v48, v48
	v_exp_f32_e32 v141, v58
	v_exp_f32_e32 v140, v59
	v_exp_f32_e32 v60, v60
	v_exp_f32_e32 v59, v61
	v_exp_f32_e32 v58, v62
	v_exp_f32_e32 v139, v32
	v_exp_f32_e32 v32, v49
	v_exp_f32_e32 v49, v33
	v_exp_f32_e32 v33, v50
	v_exp_f32_e32 v50, v34
	v_exp_f32_e32 v34, v51
	v_exp_f32_e32 v51, v35
	v_exp_f32_e32 v35, v52
	v_exp_f32_e32 v52, v36
	v_exp_f32_e32 v36, v53
	v_exp_f32_e32 v53, v37
	v_exp_f32_e32 v37, v54
	v_exp_f32_e32 v54, v38
	v_exp_f32_e32 v38, v55
	v_cvt_pk_bf16_f32 v146, v48, v32
	v_cvt_pk_bf16_f32 v147, v33, v34
	v_cvt_pk_bf16_f32 v148, v35, v36
	v_cvt_pk_bf16_f32 v149, v37, v38
	v_exp_f32_e32 v39, v39
	s_waitcnt lgkmcnt(14)
	v_mfma_f32_32x32x16_bf16 v[0:15], v[168:171], v[146:149], v[0:15]
	v_exp_f32_e32 v55, v56
	v_exp_f32_e32 v56, v57
	v_exp_f32_e32 v57, v63
	v_cvt_pk_bf16_f32 v152, v139, v49
	v_cvt_pk_bf16_f32 v153, v50, v51
	v_cvt_pk_bf16_f32 v154, v52, v53
	v_cvt_pk_bf16_f32 v155, v54, v39
	s_waitcnt lgkmcnt(12)
	v_mfma_f32_32x32x16_bf16 v[16:31], v[172:175], v[146:149], v[16:31]
	v_cvt_pk_bf16_f32 v146, v55, v56
	v_cvt_pk_bf16_f32 v147, v141, v140
	v_cvt_pk_bf16_f32 v148, v60, v59
	v_cvt_pk_bf16_f32 v149, v58, v57
	v_exp_f32_e32 v63, v40
	v_exp_f32_e32 v62, v41
	v_exp_f32_e32 v61, v42
	s_waitcnt lgkmcnt(10)
	v_mfma_f32_32x32x16_bf16 v[0:15], v[176:179], v[146:149], v[0:15]
	v_exp_f32_e32 v43, v43
	v_exp_f32_e32 v41, v44
	v_exp_f32_e32 v44, v45
	v_exp_f32_e32 v42, v46
	v_exp_f32_e32 v40, v47
	s_waitcnt lgkmcnt(8)
	v_mfma_f32_32x32x16_bf16 v[16:31], v[180:183], v[146:149], v[16:31]
	v_add_f32_e32 v224, v48, v32
	v_add_f32_e32 v225, v139, v49
	v_add_f32_e32 v224, v33, v224
	v_add_f32_e32 v225, v50, v225
	v_add_f32_e32 v224, v34, v224
	v_add_f32_e32 v225, v51, v225
	v_add_f32_e32 v224, v35, v224
	v_add_f32_e32 v225, v52, v225
	v_cvt_pk_bf16_f32 v146, v63, v62
	v_cvt_pk_bf16_f32 v147, v61, v43
	v_cvt_pk_bf16_f32 v148, v41, v44
	v_cvt_pk_bf16_f32 v149, v42, v40
	s_waitcnt lgkmcnt(6)
	v_mfma_f32_32x32x16_bf16 v[0:15], v[184:187], v[152:155], v[0:15]
	v_add_f32_e32 v224, v36, v224
	v_add_f32_e32 v225, v53, v225
	v_add_f32_e32 v224, v37, v224
	v_add_f32_e32 v225, v54, v225
	v_add_f32_e32 v224, v38, v224
	v_add_f32_e32 v225, v39, v225
	v_add_f32_e32 v224, v55, v224
	v_add_f32_e32 v225, v63, v225
	s_waitcnt lgkmcnt(4)
	v_mfma_f32_32x32x16_bf16 v[16:31], v[188:191], v[152:155], v[16:31]
	v_add_f32_e32 v224, v56, v224
	v_add_f32_e32 v225, v62, v225
	v_add_f32_e32 v224, v141, v224
	v_add_f32_e32 v225, v61, v225
	v_add_f32_e32 v224, v140, v224
	v_add_f32_e32 v225, v43, v225
	v_add_f32_e32 v224, v60, v224
	v_add_f32_e32 v225, v41, v225
	s_waitcnt lgkmcnt(2)
	v_mfma_f32_32x32x16_bf16 v[0:15], v[196:199], v[146:149], v[0:15]
	v_add_f32_e32 v224, v59, v224
	v_add_f32_e32 v225, v44, v225
	v_add_f32_e32 v224, v58, v224
	v_add_f32_e32 v225, v42, v225
	v_add_f32_e32 v224, v57, v224
	v_add_f32_e32 v225, v40, v225
	v_add_f32_e32 v224, v224, v225
	s_waitcnt lgkmcnt(0)
	v_mfma_f32_32x32x16_bf16 v[16:31], v[200:203], v[146:149], v[16:31]
	s_cbranch_vccnz .LBB0_586
	s_cmp_ge_u32 s14, s12
	s_cbranch_scc1 .Lgqa_w1_tail
	s_waitcnt vmcnt(3)
	ds_write_b128 v193, v[80:83]
	s_waitcnt vmcnt(2)
	ds_write_b128 v219, v[84:87] offset:9216
	s_branch .LBB0_586
